# grid barrier: all waiters (members and XCD leaders) poll the global arrival counter for >= nx*(gen+1) instead of the generation word, removing the last arriver's atomic-return + generation-bump hop fr
# speedup vs baseline: 1.0114x; 1.0024x over previous
.LBB0_490:
	v_readlane_b32 s16, v254, 54
	v_readlane_b32 s17, v254, 55
	v_cvt_f32_u32_e32 v0, v3
	v_sub_u32_e32 v5, 0, v3
	v_rcp_iflag_f32_e32 v0, v0
	s_nop 1
	global_atomic_add v4, v1, v236, s[16:17] sc0
	v_mul_f32_e32 v0, 0x4f7ffffe, v0
	v_cvt_u32_f32_e32 v0, v0
	v_mul_lo_u32 v5, v5, v0
	v_mul_hi_u32 v5, v0, v5
	v_add_u32_e32 v0, v0, v5
	s_waitcnt vmcnt(0)
	v_mul_hi_u32 v0, v4, v0
	v_mul_lo_u32 v5, v0, v3
	v_sub_u32_e32 v5, v4, v5
	v_add_u32_e32 v6, 1, v0
	v_cmp_ge_u32_e32 vcc, v5, v3
	v_add_u32_e32 v4, 1, v4
	s_nop 0
	v_cndmask_b32_e32 v0, v0, v6, vcc
	v_sub_u32_e32 v6, v5, v3
	v_cndmask_b32_e32 v5, v5, v6, vcc
	v_add_u32_e32 v6, 1, v0
	v_cmp_ge_u32_e32 vcc, v5, v3
	s_nop 1
	v_cndmask_b32_e32 v0, v0, v6, vcc
	v_mul_lo_u32 v5, v3, v0
	v_add_u32_e32 v3, v5, v3
	v_cmp_ne_u32_e32 vcc, v4, v3
	s_and_saveexec_b64 s[16:17], vcc
	s_xor_b64 s[16:17], exec, s[16:17]
	s_cbranch_execz .LBB0_504
	s_waitcnt lgkmcnt(0)
	v_mad_u32_u24 v5, v0, v2, v2
	v_readlane_b32 s98, v254, 56
	v_readlane_b32 s99, v254, 57
	s_nop 4
	global_load_dword v2, v1, s[98:99] sc1
	s_waitcnt vmcnt(0)
	v_cmp_gt_u32_e32 vcc, v5, v2
	s_and_saveexec_b64 s[18:19], vcc
	s_cbranch_execz .LBB0_503
	s_mov_b32 s1, 1
	s_mov_b64 s[22:23], 0
	s_branch .LBB0_494

.LBB0_496:
	global_load_dword v2, v1, s[98:99] sc1
	s_add_i32 s1, s1, 1
	s_mov_b64 s[42:43], -1
	s_waitcnt vmcnt(0)
	v_cmp_le_u32_e32 vcc, v5, v2
	s_orn2_b64 s[40:41], vcc, exec
	s_branch .LBB0_493

.LBB0_507:
	s_or_b64 exec, exec, s[18:19]
	s_waitcnt vmcnt(0)
	v_readfirstlane_b32 s1, v3
	v_sub_u32_e32 v4, 0, v2
	s_mov_b64 s[18:19], -1
	v_add_u32_e32 v3, s1, v0
	v_cvt_f32_u32_e32 v0, v2
	v_rcp_iflag_f32_e32 v0, v0
	s_nop 0
	v_mul_f32_e32 v0, 0x4f7ffffe, v0
	v_cvt_u32_f32_e32 v0, v0
	v_mul_lo_u32 v4, v4, v0
	v_mul_hi_u32 v4, v0, v4
	v_add_u32_e32 v0, v0, v4
	v_mul_hi_u32 v0, v3, v0
	v_mul_lo_u32 v4, v0, v2
	v_sub_u32_e32 v4, v3, v4
	v_cmp_ge_u32_e32 vcc, v4, v2
	v_add_u32_e32 v5, 1, v0
	v_add_u32_e32 v3, 1, v3
	v_cndmask_b32_e32 v0, v0, v5, vcc
	v_sub_u32_e32 v5, v4, v2
	v_cndmask_b32_e32 v4, v4, v5, vcc
	v_cmp_ge_u32_e32 vcc, v4, v2
	v_add_u32_e32 v4, 1, v0
	s_nop 0
	v_cndmask_b32_e32 v0, v0, v4, vcc
	v_mul_lo_u32 v4, v2, v0
	v_add_u32_e32 v2, v4, v2
	v_cmp_ne_u32_e32 vcc, v3, v2
	v_mov_b32_e32 v5, v2
	v_mov_b64_e32 v[2:3], s[80:81]
	s_and_saveexec_b64 s[16:17], vcc
	s_cbranch_execz .LBB0_519
	v_readlane_b32 s98, v254, 56
	v_readlane_b32 s99, v254, 57
	s_nop 4
	global_load_dword v2, v1, s[98:99] sc1
	s_mov_b64 s[22:23], 0
	s_waitcnt vmcnt(0)
	v_cmp_gt_u32_e32 vcc, v5, v2
	s_and_saveexec_b64 s[18:19], vcc
	s_cbranch_execz .LBB0_518
	s_mov_b32 s1, 1
	s_branch .LBB0_511

.LBB0_841:
	v_readlane_b32 s0, v254, 54
	v_readlane_b32 s1, v254, 55
	v_cvt_f32_u32_e32 v0, v3
	v_sub_u32_e32 v5, 0, v3
	v_rcp_iflag_f32_e32 v0, v0
	s_nop 1
	global_atomic_add v4, v1, v236, s[0:1] sc0
	v_mul_f32_e32 v0, 0x4f7ffffe, v0
	v_cvt_u32_f32_e32 v0, v0
	v_mul_lo_u32 v5, v5, v0
	v_mul_hi_u32 v5, v0, v5
	v_add_u32_e32 v0, v0, v5
	s_waitcnt vmcnt(0)
	v_mul_hi_u32 v0, v4, v0
	v_mul_lo_u32 v5, v0, v3
	v_sub_u32_e32 v5, v4, v5
	v_add_u32_e32 v6, 1, v0
	v_cmp_ge_u32_e32 vcc, v5, v3
	v_add_u32_e32 v4, 1, v4
	s_nop 0
	v_cndmask_b32_e32 v0, v0, v6, vcc
	v_sub_u32_e32 v6, v5, v3
	v_cndmask_b32_e32 v5, v5, v6, vcc
	v_add_u32_e32 v6, 1, v0
	v_cmp_ge_u32_e32 vcc, v5, v3
	s_nop 1
	v_cndmask_b32_e32 v0, v0, v6, vcc
	v_mul_lo_u32 v5, v3, v0
	v_add_u32_e32 v3, v5, v3
	v_cmp_ne_u32_e32 vcc, v4, v3
	s_and_saveexec_b64 s[0:1], vcc
	s_xor_b64 s[14:15], exec, s[0:1]
	s_cbranch_execz .LBB0_855
	s_waitcnt lgkmcnt(0)
	v_mad_u32_u24 v5, v0, v2, v2
	v_readlane_b32 s98, v254, 56
	v_readlane_b32 s99, v254, 57
	s_nop 4
	global_load_dword v2, v1, s[98:99] sc1
	s_waitcnt vmcnt(0)
	v_cmp_gt_u32_e32 vcc, v5, v2
	s_and_saveexec_b64 s[16:17], vcc
	s_cbranch_execz .LBB0_854
	s_mov_b32 s0, 1
	s_mov_b64 s[18:19], 0
	s_branch .LBB0_845

.LBB0_847:
	global_load_dword v2, v1, s[98:99] sc1
	s_add_i32 s0, s0, 1
	s_mov_b64 s[40:41], -1
	s_waitcnt vmcnt(0)
	v_cmp_le_u32_e32 vcc, v5, v2
	s_orn2_b64 s[38:39], vcc, exec
	s_branch .LBB0_844

.LBB0_858:
	s_or_b64 exec, exec, s[16:17]
	s_waitcnt vmcnt(0)
	v_readfirstlane_b32 s0, v3
	v_sub_u32_e32 v4, 0, v2
	s_mov_b64 s[16:17], -1
	v_add_u32_e32 v3, s0, v0
	v_cvt_f32_u32_e32 v0, v2
	v_rcp_iflag_f32_e32 v0, v0
	s_nop 0
	v_mul_f32_e32 v0, 0x4f7ffffe, v0
	v_cvt_u32_f32_e32 v0, v0
	v_mul_lo_u32 v4, v4, v0
	v_mul_hi_u32 v4, v0, v4
	v_add_u32_e32 v0, v0, v4
	v_mul_hi_u32 v0, v3, v0
	v_mul_lo_u32 v4, v0, v2
	v_sub_u32_e32 v4, v3, v4
	v_cmp_ge_u32_e32 vcc, v4, v2
	v_add_u32_e32 v5, 1, v0
	v_add_u32_e32 v3, 1, v3
	v_cndmask_b32_e32 v0, v0, v5, vcc
	v_sub_u32_e32 v5, v4, v2
	v_cndmask_b32_e32 v4, v4, v5, vcc
	v_cmp_ge_u32_e32 vcc, v4, v2
	v_add_u32_e32 v4, 1, v0
	s_nop 0
	v_cndmask_b32_e32 v0, v0, v4, vcc
	v_mul_lo_u32 v4, v2, v0
	v_add_u32_e32 v2, v4, v2
	v_cmp_ne_u32_e32 vcc, v3, v2
	v_mov_b32_e32 v5, v2
	v_mov_b64_e32 v[2:3], s[80:81]
	s_and_saveexec_b64 s[14:15], vcc
	s_cbranch_execz .LBB0_870
	v_readlane_b32 s98, v254, 56
	v_readlane_b32 s99, v254, 57
	s_nop 4
	global_load_dword v2, v1, s[98:99] sc1
	s_mov_b64 s[18:19], 0
	s_waitcnt vmcnt(0)
	v_cmp_gt_u32_e32 vcc, v5, v2
	s_and_saveexec_b64 s[16:17], vcc
	s_cbranch_execz .LBB0_869
	s_mov_b32 s0, 1
	s_branch .LBB0_862
